# attention softmax VALU trim: float position counter (7 fewer VALU per tile), lsum pk_add->scalar adds, 8 pk-hazard s_nops dropped
# baseline (speedup 1.0000x reference)
.LBB0_366:
	v_lshl_add_u32 v117, s14, 6, v155
	v_cvt_f32_i32_e32 v117, v117
	v_sub_f32_e32 v117, v116, v117
	s_add_i32 s12, s14, 2
	s_mov_b32 s13, 1
	s_mov_b32 s1, 0
	s_mov_b32 s0, 0

.LBB0_371:
	v_add_f32_e32 v117, 0xc2800000, v117
	s_and_b64 vcc, exec, s[0:1]
	s_cbranch_vccz .LBB0_376
	s_branch .LBB0_377

.LBB0_374:
	s_lshl_b32 s2, s14, 15
	s_add_i32 s2, s2, 0
	v_add_u32_e32 v170, s2, v135
	v_add_u32_e32 v178, s2, v136
	v_add_u32_e32 v186, s2, v137
	v_add_u32_e32 v194, s2, v138
	ds_read_b128 v[84:87], v170
	ds_read_b128 v[88:91], v170 offset:1024
	ds_read_b128 v[92:95], v178
	ds_read_b128 v[96:99], v178 offset:1024
	ds_read_b128 v[118:121], v186
	ds_read_b128 v[122:125], v186 offset:1024
	ds_read_b128 v[158:161], v194
	ds_read_b128 v[162:165], v194 offset:1024
	ds_read_b128 v[166:169], v170 offset:2048
	ds_read_b128 v[170:173], v170 offset:3072
	ds_read_b128 v[174:177], v178 offset:2048
	ds_read_b128 v[178:181], v178 offset:3072
	ds_read_b128 v[182:185], v186 offset:2048
	ds_read_b128 v[186:189], v186 offset:3072
	ds_read_b128 v[190:193], v194 offset:2048
	ds_read_b128 v[194:197], v194 offset:3072
	s_waitcnt lgkmcnt(0)
	v_mfma_f32_16x16x32_bf16 v[84:87], v[84:87], v[0:3], v[52:55]
	v_mfma_f32_16x16x32_bf16 v[118:121], v[118:121], v[8:11], v[52:55]
	v_mfma_f32_16x16x32_bf16 v[88:91], v[88:91], v[0:3], v[52:55]
	v_mfma_f32_16x16x32_bf16 v[122:125], v[122:125], v[8:11], v[52:55]
	v_mfma_f32_16x16x32_bf16 v[166:169], v[166:169], v[0:3], v[52:55]
	v_mfma_f32_16x16x32_bf16 v[182:185], v[182:185], v[8:11], v[52:55]
	v_mfma_f32_16x16x32_bf16 v[170:173], v[170:173], v[0:3], v[52:55]
	v_mfma_f32_16x16x32_bf16 v[186:189], v[186:189], v[8:11], v[52:55]
	v_mfma_f32_16x16x32_bf16 v[84:87], v[92:95], v[4:7], v[84:87]
	v_mfma_f32_16x16x32_bf16 v[92:95], v[158:161], v[12:15], v[118:121]
	v_mfma_f32_16x16x32_bf16 v[88:91], v[96:99], v[4:7], v[88:91]
	v_mfma_f32_16x16x32_bf16 v[96:99], v[162:165], v[12:15], v[122:125]
	v_mfma_f32_16x16x32_bf16 v[118:121], v[174:177], v[4:7], v[166:169]
	v_mfma_f32_16x16x32_bf16 v[122:125], v[190:193], v[12:15], v[182:185]
	v_mfma_f32_16x16x32_bf16 v[158:161], v[178:181], v[4:7], v[170:173]
	v_mfma_f32_16x16x32_bf16 v[162:165], v[194:197], v[12:15], v[186:189]
	v_add_f32_e32 v170, 0x42100000, v117
	v_fma_f32 v84, -v157, |v170|, v84
	v_add_f32_e32 v168, -1.0, v170
	v_fma_f32 v92, -v157, |v170|, v92
	v_exp_f32_e32 v166, v84
	v_fma_f32 v84, -v157, |v168|, v85
	v_exp_f32_e32 v167, v92
	v_exp_f32_e32 v92, v84
	v_fma_f32 v84, -v157, |v168|, v93
	v_exp_f32_e32 v93, v84
	v_add_f32_e32 v84, -2.0, v170
	v_fma_f32 v85, -v157, |v84|, v86
	v_fma_f32 v84, -v157, |v84|, v94
	v_exp_f32_e32 v169, v84
	v_add_f32_e32 v84, 0xc0400000, v170
	v_exp_f32_e32 v168, v85
	v_fma_f32 v85, -v157, |v84|, v87
	v_fma_f32 v84, -v157, |v84|, v95
	v_exp_f32_e32 v95, v84
	v_add_f32_e32 v84, 0x42000000, v117
	v_exp_f32_e32 v94, v85
	v_fma_f32 v85, -v157, |v84|, v88
	v_exp_f32_e32 v170, v85
	v_fma_f32 v85, -v157, |v84|, v96
	v_exp_f32_e32 v171, v85
	v_add_f32_e32 v85, -1.0, v84
	v_fma_f32 v86, -v157, |v85|, v89
	v_fma_f32 v85, -v157, |v85|, v97
	v_exp_f32_e32 v97, v85
	v_add_f32_e32 v85, -2.0, v84
	v_exp_f32_e32 v96, v86
	v_fma_f32 v86, -v157, |v85|, v90
	v_fma_f32 v85, -v157, |v85|, v98
	v_add_f32_e32 v84, 0xc0400000, v84
	v_exp_f32_e32 v173, v85
	v_fma_f32 v85, -v157, |v84|, v91
	v_fma_f32 v84, -v157, |v84|, v99
	v_exp_f32_e32 v90, v85
	v_exp_f32_e32 v91, v84
	v_add_f32_e32 v84, v114, v166
	v_add_f32_e32 v85, v115, v167
	v_exp_f32_e32 v172, v86
	v_add_f32_e32 v84, v84, v92
	v_add_f32_e32 v85, v85, v93
	v_add_f32_e32 v84, v84, v168
	v_add_f32_e32 v85, v85, v169
	v_cvt_pk_bf16_f32 v88, v167, v93
	v_cvt_pk_bf16_f32 v86, v170, v96
	v_cvt_pk_bf16_f32 v87, v172, v90
	v_add_f32_e32 v84, v84, v94
	v_add_f32_e32 v85, v85, v95
	v_add_f32_e32 v84, v84, v170
	v_add_f32_e32 v85, v85, v171
	v_add_f32_e32 v84, v84, v96
	v_add_f32_e32 v85, v85, v97
	v_add_f32_e32 v84, v84, v172
	v_add_f32_e32 v85, v85, v173
	v_add_f32_e32 v98, v84, v90
	v_add_f32_e32 v99, v85, v91
	v_cvt_pk_bf16_f32 v84, v166, v92
	v_cvt_pk_bf16_f32 v90, v171, v97
	v_cvt_pk_bf16_f32 v85, v168, v94
	v_cvt_pk_bf16_f32 v89, v169, v95
	v_add_f32_e32 v92, 4.0, v117
	v_fma_f32 v93, -v157, |v92|, v118
	v_exp_f32_e32 v96, v93
	v_fma_f32 v93, -v157, |v92|, v122
	v_exp_f32_e32 v97, v93
	v_add_f32_e32 v93, -1.0, v92
	v_fma_f32 v94, -v157, |v93|, v119
	v_fma_f32 v93, -v157, |v93|, v123
	v_exp_f32_e32 v119, v93
	v_add_f32_e32 v93, -2.0, v92
	v_exp_f32_e32 v118, v94
	v_fma_f32 v94, -v157, |v93|, v120
	v_exp_f32_e32 v122, v94
	v_fma_f32 v93, -v157, |v93|, v124
	v_add_f32_e32 v92, 0xc0400000, v92
	v_exp_f32_e32 v123, v93
	v_fma_f32 v93, -v157, |v92|, v121
	v_fma_f32 v92, -v157, |v92|, v125
	v_mov_b32_e32 v94, v117
	v_exp_f32_e32 v121, v92
	v_fma_f32 v92, -v157, |v94|, v158
	v_exp_f32_e32 v124, v92
	v_fma_f32 v92, -v157, |v94|, v162
	v_exp_f32_e32 v125, v92
	v_add_f32_e32 v92, -1.0, v94
	v_exp_f32_e32 v120, v93
	v_fma_f32 v93, -v157, |v92|, v159
	v_fma_f32 v92, -v157, |v92|, v163
	v_exp_f32_e32 v159, v92
	v_add_f32_e32 v92, -2.0, v94
	v_exp_f32_e32 v158, v93
	v_fma_f32 v93, -v157, |v92|, v160
	v_fma_f32 v92, -v157, |v92|, v164
	v_exp_f32_e32 v162, v93
	v_exp_f32_e32 v163, v92
	v_add_f32_e32 v92, v98, v96
	v_add_f32_e32 v93, v99, v97
	v_add_f32_e32 v94, 0xc0400000, v94
	v_add_f32_e32 v92, v92, v118
	v_add_f32_e32 v93, v93, v119
	v_fma_f32 v95, -v157, |v94|, v161
	v_add_f32_e32 v92, v92, v122
	v_add_f32_e32 v93, v93, v123
	v_fma_f32 v94, -v157, |v94|, v165
	v_add_f32_e32 v92, v92, v120
	v_add_f32_e32 v93, v93, v121
	v_exp_f32_e32 v98, v95
	v_exp_f32_e32 v99, v94
	v_add_f32_e32 v92, v92, v124
	v_add_f32_e32 v93, v93, v125
	v_cvt_pk_bf16_f32 v91, v173, v91
	v_cvt_pk_bf16_f32 v94, v124, v158
	v_cvt_pk_bf16_f32 v95, v162, v98
	v_add_f32_e32 v92, v92, v158
	v_add_f32_e32 v93, v93, v159
	v_add_f32_e32 v92, v92, v162
	v_add_f32_e32 v93, v93, v163
	v_add_f32_e32 v114, v92, v98
	v_add_f32_e32 v115, v93, v99
	v_cvt_pk_bf16_f32 v92, v96, v118
	v_cvt_pk_bf16_f32 v93, v122, v120
	v_cvt_pk_bf16_f32 v96, v97, v119
	v_cvt_pk_bf16_f32 v97, v123, v121
	v_cvt_pk_bf16_f32 v98, v125, v159
	v_cvt_pk_bf16_f32 v99, v163, v99
	s_or_b64 s[18:19], s[54:55], s[0:1]
	s_and_b64 vcc, exec, s[18:19]
	s_cbranch_vccnz .LBB0_371
.LBB0_375:
	s_lshl_b32 s2, s14, 15
	s_add_i32 s2, s2, 0
	v_add_u32_e32 v178, s2, v139
	v_add_u32_e32 v210, s2, v154
	ds_read_b128 v[118:121], v178 offset:16384
	ds_read_b128 v[122:125], v178 offset:16896
	ds_read_b128 v[158:161], v178 offset:17408
	ds_read_b128 v[162:165], v178 offset:17920
	ds_read_b128 v[166:169], v178 offset:18432
	ds_read_b128 v[170:173], v178 offset:18944
	ds_read_b128 v[174:177], v178 offset:19456
	ds_read_b128 v[178:181], v178 offset:19968
	ds_read_b128 v[182:185], v210 offset:16384
	ds_read_b128 v[186:189], v210 offset:16896
	ds_read_b128 v[190:193], v210 offset:17408
	ds_read_b128 v[194:197], v210 offset:17920
	ds_read_b128 v[198:201], v210 offset:18432
	ds_read_b128 v[202:205], v210 offset:18944
	ds_read_b128 v[206:209], v210 offset:19456
	ds_read_b128 v[228:231], v210 offset:19968
	s_waitcnt lgkmcnt(0)
	v_mfma_f32_16x16x32_bf16 v[56:59], v[118:121], v[84:87], v[56:59]
	v_mfma_f32_16x16x32_bf16 v[48:51], v[118:121], v[88:91], v[48:51]
	v_mfma_f32_16x16x32_bf16 v[60:63], v[122:125], v[84:87], v[60:63]
	v_mfma_f32_16x16x32_bf16 v[44:47], v[122:125], v[88:91], v[44:47]
	v_mfma_f32_16x16x32_bf16 v[64:67], v[158:161], v[84:87], v[64:67]
	v_mfma_f32_16x16x32_bf16 v[40:43], v[158:161], v[88:91], v[40:43]
	v_mfma_f32_16x16x32_bf16 v[68:71], v[162:165], v[84:87], v[68:71]
	v_mfma_f32_16x16x32_bf16 v[36:39], v[162:165], v[88:91], v[36:39]
	v_mfma_f32_16x16x32_bf16 v[72:75], v[166:169], v[84:87], v[72:75]
	v_mfma_f32_16x16x32_bf16 v[32:35], v[166:169], v[88:91], v[32:35]
	v_mfma_f32_16x16x32_bf16 v[76:79], v[170:173], v[84:87], v[76:79]
	v_mfma_f32_16x16x32_bf16 v[24:27], v[170:173], v[88:91], v[24:27]
	v_mfma_f32_16x16x32_bf16 v[80:83], v[174:177], v[84:87], v[80:83]
	v_mfma_f32_16x16x32_bf16 v[20:23], v[174:177], v[88:91], v[20:23]
	v_mfma_f32_16x16x32_bf16 v[28:31], v[178:181], v[84:87], v[28:31]
	v_mfma_f32_16x16x32_bf16 v[16:19], v[178:181], v[88:91], v[16:19]
	v_mfma_f32_16x16x32_bf16 v[56:59], v[182:185], v[92:95], v[56:59]
	v_mfma_f32_16x16x32_bf16 v[48:51], v[182:185], v[96:99], v[48:51]
	v_mfma_f32_16x16x32_bf16 v[60:63], v[186:189], v[92:95], v[60:63]
	v_mfma_f32_16x16x32_bf16 v[44:47], v[186:189], v[96:99], v[44:47]
	v_mfma_f32_16x16x32_bf16 v[64:67], v[190:193], v[92:95], v[64:67]
	v_mfma_f32_16x16x32_bf16 v[40:43], v[190:193], v[96:99], v[40:43]
	v_mfma_f32_16x16x32_bf16 v[68:71], v[194:197], v[92:95], v[68:71]
	v_mfma_f32_16x16x32_bf16 v[36:39], v[194:197], v[96:99], v[36:39]
	v_mfma_f32_16x16x32_bf16 v[72:75], v[198:201], v[92:95], v[72:75]
	v_mfma_f32_16x16x32_bf16 v[32:35], v[198:201], v[96:99], v[32:35]
	v_mfma_f32_16x16x32_bf16 v[76:79], v[202:205], v[92:95], v[76:79]
	v_mfma_f32_16x16x32_bf16 v[24:27], v[202:205], v[96:99], v[24:27]
	v_mfma_f32_16x16x32_bf16 v[80:83], v[206:209], v[92:95], v[80:83]
	v_mfma_f32_16x16x32_bf16 v[20:23], v[206:209], v[96:99], v[20:23]
	v_mfma_f32_16x16x32_bf16 v[28:31], v[228:231], v[92:95], v[28:31]
	v_mfma_f32_16x16x32_bf16 v[16:19], v[228:231], v[96:99], v[16:19]
	v_add_f32_e32 v117, 0xc2800000, v117
	s_and_b64 vcc, exec, s[0:1]
	s_cbranch_vccnz .LBB0_377
